# MLA key loop stagger variant: waves 0-3 delayed (s_sleep 8) after each stage barrier
# baseline (speedup 1.0000x reference)
; #define AT_SB __builtin_amdgcn_sched_barrier(0);
; template <int DQK, int MODE, bool QN, bool KN> ...
;     ...
;   for (int sg = 0; sg < nsg; sg += 2) {
;     AT_SB AT_GLOAD(rk0, rv0, sg + 2)
;     AT_SB compute(2 * sg, 0); compute(2 * sg + 1, 0); AT_SB
.LBB0_1198:
	s_cmp_lg_u32 s101, 0
	s_cbranch_scc1 .Lstg_a
	s_sleep 8

; #define AT_SB __builtin_amdgcn_sched_barrier(0);
; template <int DQK, int MODE, bool QN, bool KN> ...
;     ...
;     AT_SWRITE(rk1, rv1, 1)
;     if (MODE == 2) { if (__syncthreads_and(carry < 1.17549435e-38f)) break; } else { __syncthreads(); }
;     AT_SB AT_GLOAD(rk1, rv1, sg + 3)
.LBB0_1218:
	s_or_b64 exec, exec, s[2:3]
	s_waitcnt vmcnt(9)
	ds_write_b128 v244, v[184:187] offset:43008
	s_waitcnt vmcnt(8)
	ds_write_b128 v245, v[188:191] offset:43008
	s_waitcnt vmcnt(7)
	ds_write_b128 v246, v[192:195] offset:43008
	s_waitcnt vmcnt(6)
	ds_write_b128 v250, v[196:199]
	s_waitcnt vmcnt(5)
	ds_write_b128 v250, v[200:203] offset:4096
	s_waitcnt lgkmcnt(0)
	s_barrier
	s_cmp_lg_u32 s101, 0
	s_cbranch_scc1 .Lstg_b
	s_sleep 8
